# v47 plus acquire invalidate issued at barrier entry (right after the arrival atomic, every wave already drained and parked) instead of after the release is observed: its latency overlaps the wait
# speedup vs baseline: 1.0257x; 1.0120x over previous
.LBB0_95:
	s_getreg_b32 s98, hwreg(HW_REG_XCC_ID, 0, 4)
	s_lshl_b32 s98, s98, 8
	v_mov_b32_e32 v1, 0x21160
	ds_read_b64 v[2:3], v1
	v_mov_b32_e32 v4, s98
	v_add_u32_e32 v4, 0x5400, v4
	v_mov_b32_e32 v5, 1
	global_atomic_add v6, v4, v5, s[54:55] sc0
	buffer_inv sc1
	v_add_u32_e32 v7, 0x1000, v4
	s_waitcnt lgkmcnt(0)
	v_mul_u32_u24_e32 v2, 1, v2
	v_mul_u32_u24_e32 v3, 1, v3
	s_waitcnt vmcnt(1)
	v_add_u32_e32 v6, 1, v6
	v_cmp_ne_u32_e32 vcc, v6, v2
	s_cbranch_vccnz .Lgb4_1_follow
	buffer_wbl2 sc1
	s_waitcnt vmcnt(0)
	v_mov_b32_e32 v4, 0x7400
	global_atomic_add v6, v4, v5, s[54:55] sc0
	s_waitcnt vmcnt(0)
	v_add_u32_e32 v6, 1, v6
	v_cmp_ne_u32_e32 vcc, v6, v3
	s_cbranch_vccnz .Lgb4_1_follow
	v_mov_b32_e32 v4, 0x6400
	global_atomic_add v4, v5, s[54:55]
	global_atomic_add v4, v5, s[54:55] offset:256
	global_atomic_add v4, v5, s[54:55] offset:512
	global_atomic_add v4, v5, s[54:55] offset:768
	global_atomic_add v4, v5, s[54:55] offset:1024
	global_atomic_add v4, v5, s[54:55] offset:1280
	global_atomic_add v4, v5, s[54:55] offset:1536
	global_atomic_add v4, v5, s[54:55] offset:1792
	global_atomic_add v4, v5, s[54:55] offset:2048
	global_atomic_add v4, v5, s[54:55] offset:2304
	global_atomic_add v4, v5, s[54:55] offset:2560
	global_atomic_add v4, v5, s[54:55] offset:2816
	global_atomic_add v4, v5, s[54:55] offset:3072
	global_atomic_add v4, v5, s[54:55] offset:3328
	global_atomic_add v4, v5, s[54:55] offset:3584
	global_atomic_add v4, v5, s[54:55] offset:3840
	s_branch .Lgb4_1_acq

.Lgb4_1_gen:
	global_load_dword v6, v7, s[54:55] sc1
	s_waitcnt vmcnt(0)
	v_cmp_ge_u32_e32 vcc, v6, v2
	s_cbranch_vccnz .Lgb4_1_acq
	s_add_i32 s99, s99, 1
	s_cmp_gt_u32 s99, 0x40000
	s_cbranch_scc1 .Lgb4_1_acq
	s_sleep 1
	s_branch .Lgb4_1_gen
.Lgb4_1_acq:
	s_waitcnt vmcnt(0)
.LBB0_131:
	s_or_b64 exec, exec, s[6:7]
	v_mov_b32_e32 v10, v0
	s_cmpk_lt_i32 s38, 0x1e0
	s_waitcnt lgkmcnt(0)
	s_barrier
	s_cselect_b64 s[4:5], -1, 0
	s_cmpk_gt_i32 s38, 0x1df
	v_readfirstlane_b32 s0, v10
	s_cbranch_scc1 .LBB0_133
	s_ashr_i32 s1, s38, 31
	s_lshr_b32 s1, s1, 29
	s_add_i32 s1, s38, s1
	s_ashr_i32 s3, s1, 3
	s_and_b32 s1, s1, -8
	s_sub_i32 s1, s38, s1
	s_cmp_lt_i32 s1, 0
	s_cselect_b32 s6, 61, 60
	s_mul_i32 s1, s1, s6
	s_add_i32 s1, s1, s3
	s_mul_hi_i32 s3, s1, 0x88888889
	s_add_i32 s3, s3, s1
	s_lshr_b32 s6, s3, 31
	s_ashr_i32 s3, s3, 5
	s_add_i32 s3, s3, s6
	s_mul_i32 s6, s3, 6
	s_mul_i32 s3, s3, 60
	s_sub_i32 s1, s1, s3
	s_bfe_i32 s3, s1, 0x80000
	s_mul_i32 s3, s3, 43
	s_bfe_u32 s7, s3, 0x1000f
	s_bfe_u32 s3, s3, 0x80008
	s_add_i32 s3, s3, s7
	s_mul_i32 s7, s3, 6
	s_sub_i32 s1, s1, s7
	s_sext_i32_i8 s1, s1
	s_add_i32 s70, s6, s1
	s_sext_i32_i8 s8, s3

.LBB0_236:
	s_getreg_b32 s98, hwreg(HW_REG_XCC_ID, 0, 4)
	s_lshl_b32 s98, s98, 8
	v_mov_b32_e32 v1, 0x21160
	ds_read_b64 v[2:3], v1
	v_mov_b32_e32 v4, s98
	v_add_u32_e32 v4, 0x5400, v4
	v_mov_b32_e32 v5, 1
	global_atomic_add v6, v4, v5, s[54:55] sc0
	buffer_inv sc1
	v_add_u32_e32 v7, 0x1000, v4
	s_waitcnt lgkmcnt(0)
	v_mul_u32_u24_e32 v2, 2, v2
	v_mul_u32_u24_e32 v3, 2, v3
	s_waitcnt vmcnt(1)
	v_add_u32_e32 v6, 1, v6
	v_cmp_ne_u32_e32 vcc, v6, v2
	s_cbranch_vccnz .Lgb4_2_follow
	buffer_wbl2 sc1
	s_waitcnt vmcnt(0)
	v_mov_b32_e32 v4, 0x7400
	global_atomic_add v6, v4, v5, s[54:55] sc0
	s_waitcnt vmcnt(0)
	v_add_u32_e32 v6, 1, v6
	v_cmp_ne_u32_e32 vcc, v6, v3
	s_cbranch_vccnz .Lgb4_2_follow
	v_mov_b32_e32 v4, 0x6400
	global_atomic_add v4, v5, s[54:55]
	global_atomic_add v4, v5, s[54:55] offset:256
	global_atomic_add v4, v5, s[54:55] offset:512
	global_atomic_add v4, v5, s[54:55] offset:768
	global_atomic_add v4, v5, s[54:55] offset:1024
	global_atomic_add v4, v5, s[54:55] offset:1280
	global_atomic_add v4, v5, s[54:55] offset:1536
	global_atomic_add v4, v5, s[54:55] offset:1792
	global_atomic_add v4, v5, s[54:55] offset:2048
	global_atomic_add v4, v5, s[54:55] offset:2304
	global_atomic_add v4, v5, s[54:55] offset:2560
	global_atomic_add v4, v5, s[54:55] offset:2816
	global_atomic_add v4, v5, s[54:55] offset:3072
	global_atomic_add v4, v5, s[54:55] offset:3328
	global_atomic_add v4, v5, s[54:55] offset:3584
	global_atomic_add v4, v5, s[54:55] offset:3840
	s_branch .Lgb4_2_acq

.Lgb4_2_gen:
	global_load_dword v6, v7, s[54:55] sc1
	s_waitcnt vmcnt(0)
	v_cmp_ge_u32_e32 vcc, v6, v2
	s_cbranch_vccnz .Lgb4_2_acq
	s_add_i32 s99, s99, 1
	s_cmp_gt_u32 s99, 0x40000
	s_cbranch_scc1 .Lgb4_2_acq
	s_sleep 1
	s_branch .Lgb4_2_gen
.Lgb4_2_acq:
	s_waitcnt vmcnt(0)
.LBB0_272:
	s_or_b64 exec, exec, s[6:7]
	s_add_u32 s92, s54, 0xa000000
	s_addc_u32 s93, s55, 0
	s_add_u32 s82, s54, 0x2400
	s_addc_u32 s83, s55, 0
	s_add_u32 s80, s54, 0xd000000
	v_mov_b32_e32 v130, v0
	s_addc_u32 s81, s55, 0
	s_waitcnt lgkmcnt(0)
	s_barrier
	s_mov_b64 s[4:5], -1
	s_andn2_b64 vcc, exec, s[16:17]
	v_bfe_u32 v88, v130, 4, 2
	v_and_b32_e32 v135, 15, v130
	v_lshlrev_b32_e32 v89, 4, v130
	v_ashrrev_i32_e32 v1, 4, v130
	v_lshlrev_b32_e32 v141, 2, v130
	v_cmp_eq_u32_e64 s[34:35], 0, v130
	s_cbranch_vccnz .LBB0_279
	v_add_u32_e32 v4, 0x200, v130
	v_and_b32_e32 v66, 0xf0, v89
	v_ashrrev_i32_e32 v90, 4, v4
	v_add_u32_e32 v4, 0x400, v130
	s_add_i32 s0, 0, 0x11000
	v_and_b32_e32 v7, 12, v141
	v_ashrrev_i32_e32 v91, 4, v4
	v_add_u32_e32 v4, 0x600, v130
	v_add_u32_e32 v5, s0, v66
	v_lshlrev_b32_e32 v93, 1, v7
	v_sub_u32_e32 v7, 0xff, v1
	s_movk_i32 s0, 0x110
	v_ashrrev_i32_e32 v92, 4, v4
	v_add_u32_e32 v4, 0, v66
	v_cvt_f32_i32_e32 v94, v7
	v_mul_lo_u32 v7, v1, s0
	v_add_u32_e32 v96, v4, v7
	v_add_u32_e32 v97, v5, v7
	v_sub_u32_e32 v7, 0xff, v90
	v_cvt_f32_i32_e32 v98, v7
	v_mul_lo_u32 v7, v90, s0
	v_add_u32_e32 v100, v4, v7
	v_add_u32_e32 v101, v5, v7
	v_sub_u32_e32 v7, 0xff, v91
	v_cvt_f32_i32_e32 v102, v7
	v_mul_lo_u32 v7, v91, s0
	v_add_u32_e32 v104, v4, v7
	v_add_u32_e32 v105, v5, v7
	v_sub_u32_e32 v7, 0xff, v92
	v_cvt_f32_i32_e32 v106, v7
	v_mul_lo_u32 v7, v92, s0
	v_add_u32_e32 v108, v4, v7
	v_add_u32_e32 v109, v5, v7
	v_add_u32_e32 v4, 0x80, v1
	v_sub_u32_e32 v5, 0x7f, v1
	v_cvt_f32_i32_e32 v112, v5
	v_cvt_f32_i32_e32 v113, v4
	v_add_u32_e32 v4, 0x80, v90
	v_sub_u32_e32 v5, 0x7f, v90
	s_lshl_b32 s3, s38, 1
	v_cvt_f32_i32_e32 v114, v5
	v_cvt_f32_i32_e32 v115, v4
	v_add_u32_e32 v4, 0x80, v91
	v_sub_u32_e32 v5, 0x7f, v91
	s_add_i32 s36, s3, 0xfffffec0
	v_cvt_f32_i32_e32 v116, v5
	v_cvt_f32_i32_e32 v117, v4
	v_add_u32_e32 v4, 0x80, v92
	v_sub_u32_e32 v5, 0x7f, v92
	s_bfe_u32 s18, s38, 0x20002
	v_readlane_b32 s0, v242, 0
	v_bfe_u32 v6, v130, 2, 2
	v_cvt_f32_i32_e32 v95, v1
	v_cvt_f32_i32_e32 v99, v90
	v_cvt_f32_i32_e32 v103, v91
	v_cvt_f32_i32_e32 v107, v92
	v_cvt_f32_i32_e32 v118, v5
	v_cvt_f32_i32_e32 v119, v4
	s_lshl_b32 s16, s18, 2
	v_readlane_b32 s4, v242, 4
	v_mov_b32_e32 v67, 0
	v_lshl_or_b32 v6, v88, 3, v6
	v_lshlrev_b32_e32 v4, 7, v135
	v_readlane_b32 s5, v242, 5
	s_add_u32 s16, s4, s16
	s_mov_b32 s73, 0
	v_lshl_add_u64 v[2:3], s[68:69], 0, v[66:67]
	v_mul_u32_u24_e32 v110, 0x110, v6
	v_lshlrev_b32_e32 v6, 2, v88
	v_or_b32_e32 v8, 0x800, v4
	v_or_b32_e32 v10, 0x1000, v4
	v_or_b32_e32 v12, 0x1800, v4
	v_or_b32_e32 v14, 0x2000, v4
	v_or_b32_e32 v16, 0x2800, v4
	v_or_b32_e32 v18, 0x3000, v4
	v_or_b32_e32 v20, 0x3800, v4
	v_readlane_b32 s1, v242, 1
	v_readlane_b32 s10, v242, 10
	v_readlane_b32 s11, v242, 11
	s_addc_u32 s17, s5, 0
	s_lshl_b32 s72, s18, 8
	v_add3_u32 v111, 0, v93, v110
	v_lshl_add_u64 v[68:69], v[2:3], 0, s[72:73]
	s_mov_b64 s[18:19], -1
	s_mov_b32 s0, 0xbfb8aa3b
	s_mov_b32 s1, 0x42ce8ed0
	s_mov_b32 s10, 0xc2b17218
	s_mov_b32 s11, 0x7f800000
	s_mov_b32 s24, 0x3f2aaaab
	v_mov_b32_e32 v120, 0x3ecc95a3
	s_mov_b32 s25, 0x3f317218
	s_mov_b32 s26, 0x33800000
	s_movk_i32 s27, 0x1400
	s_mov_b32 s28, 0x8800
	v_lshlrev_b32_e32 v70, 1, v6
	v_lshlrev_b32_e32 v72, 1, v4
	v_lshlrev_b32_e32 v74, 1, v8
	v_lshlrev_b32_e32 v76, 1, v10
	v_lshlrev_b32_e32 v66, 1, v12
	v_lshlrev_b32_e32 v78, 1, v14
	v_lshlrev_b32_e32 v80, 1, v16
	v_lshlrev_b32_e32 v82, 1, v18
	v_lshlrev_b32_e32 v84, 1, v20
	v_mov_b32_e32 v121, 0x7f800000
	v_mov_b32_e32 v86, 0x3f317218
	v_mov_b32_e32 v71, v67
	v_mov_b32_e32 v73, v67
	v_mov_b32_e32 v75, v67
	v_mov_b32_e32 v77, v67
	s_mov_b32 s5, 0
	v_readlane_b32 s2, v242, 2
	v_readlane_b32 s3, v242, 3
	v_readlane_b32 s6, v242, 6
	v_readlane_b32 s7, v242, 7
	v_readlane_b32 s8, v242, 8
	v_readlane_b32 s9, v242, 9
	v_readlane_b32 s12, v242, 12
	v_readlane_b32 s13, v242, 13
	v_readlane_b32 s14, v242, 14
	v_readlane_b32 s15, v242, 15
	s_branch .LBB0_275

.LBB0_324:
	s_getreg_b32 s98, hwreg(HW_REG_XCC_ID, 0, 4)
	s_lshl_b32 s98, s98, 8
	v_mov_b32_e32 v1, 0x21160
	ds_read_b64 v[2:3], v1
	v_mov_b32_e32 v4, s98
	v_add_u32_e32 v4, 0x5400, v4
	v_mov_b32_e32 v5, 1
	global_atomic_add v6, v4, v5, s[54:55] sc0
	buffer_inv sc1
	v_add_u32_e32 v7, 0x1000, v4
	s_waitcnt lgkmcnt(0)
	v_mul_u32_u24_e32 v2, 3, v2
	v_mul_u32_u24_e32 v3, 3, v3
	s_waitcnt vmcnt(1)
	v_add_u32_e32 v6, 1, v6
	v_cmp_ne_u32_e32 vcc, v6, v2
	s_cbranch_vccnz .Lgb4_3_follow
	buffer_wbl2 sc1
	s_waitcnt vmcnt(0)
	v_mov_b32_e32 v4, 0x7400
	global_atomic_add v6, v4, v5, s[54:55] sc0
	s_waitcnt vmcnt(0)
	v_add_u32_e32 v6, 1, v6
	v_cmp_ne_u32_e32 vcc, v6, v3
	s_cbranch_vccnz .Lgb4_3_follow
	v_mov_b32_e32 v4, 0x6400
	global_atomic_add v4, v5, s[54:55]
	global_atomic_add v4, v5, s[54:55] offset:256
	global_atomic_add v4, v5, s[54:55] offset:512
	global_atomic_add v4, v5, s[54:55] offset:768
	global_atomic_add v4, v5, s[54:55] offset:1024
	global_atomic_add v4, v5, s[54:55] offset:1280
	global_atomic_add v4, v5, s[54:55] offset:1536
	global_atomic_add v4, v5, s[54:55] offset:1792
	global_atomic_add v4, v5, s[54:55] offset:2048
	global_atomic_add v4, v5, s[54:55] offset:2304
	global_atomic_add v4, v5, s[54:55] offset:2560
	global_atomic_add v4, v5, s[54:55] offset:2816
	global_atomic_add v4, v5, s[54:55] offset:3072
	global_atomic_add v4, v5, s[54:55] offset:3328
	global_atomic_add v4, v5, s[54:55] offset:3584
	global_atomic_add v4, v5, s[54:55] offset:3840
	s_branch .Lgb4_3_acq

.Lgb4_3_gen:
	global_load_dword v6, v7, s[54:55] sc1
	s_waitcnt vmcnt(0)
	v_cmp_ge_u32_e32 vcc, v6, v2
	s_cbranch_vccnz .Lgb4_3_acq
	s_add_i32 s99, s99, 1
	s_cmp_gt_u32 s99, 0x40000
	s_cbranch_scc1 .Lgb4_3_acq
	s_sleep 1
	s_branch .Lgb4_3_gen
.Lgb4_3_acq:
	s_waitcnt vmcnt(0)
.LBB0_360:
	s_or_b64 exec, exec, s[6:7]
	s_add_u32 s60, s54, 0xb800000
	s_addc_u32 s61, s55, 0
	s_cmpk_gt_i32 s38, 0x7f
	s_waitcnt lgkmcnt(0)
	s_barrier
	s_cbranch_scc0 .LBB0_365
	s_cmpk_lt_u32 s38, 0x80
	s_mov_b64 s[14:15], 0
	s_cbranch_scc0 .LBB0_366
	s_and_b32 s0, s38, 3
	s_lshl_b32 s1, s0, 2
	v_readlane_b32 s16, v242, 0
	v_mov_b32_e32 v4, v0
	v_mov_b32_e32 v1, s1
	v_readlane_b32 s20, v242, 4
	v_readlane_b32 s21, v242, 5
	s_nop 4
	global_load_dword v2, v1, s[20:21]
	global_load_dword v5, v1, s[20:21] offset:16
	s_mov_b32 s7, 0xbfb8aa3b
	s_mov_b32 s8, 0x42ce8ed0
	s_mov_b32 s9, 0xc2b17218
	v_mov_b32_e32 v8, 0x7f800000
	s_mov_b32 s10, 0x3f2aaaab
	s_mov_b32 s6, 0x3f317218
	v_mov_b32_e32 v9, 0x3ecc95a3
	s_mov_b32 s4, 0x7f800000
	s_mov_b32 s5, 0x33800000
	v_mov_b32_e32 v10, 0x3f2aaada
	s_lshl_b32 s1, s38, 6
	s_add_i32 s1, s1, 0x7fffe000
	v_readfirstlane_b32 s11, v4
	s_and_b32 s3, s1, 0x7fffff00
	s_ashr_i32 s1, s11, 6
	v_and_b32_e32 v12, 15, v4
	s_lshl_b32 s16, s0, 8
	v_readlane_b32 s18, v242, 2
	v_mov_b32_e32 v3, 0
	s_movk_i32 s18, 0x1400
	v_readlane_b32 s17, v242, 1
	s_mov_b32 s17, 0
	v_bfe_u32 v13, v4, 4, 2
	v_and_b32_e32 v1, 63, v4
	v_readlane_b32 s19, v242, 3
	v_readlane_b32 s22, v242, 6
	v_readlane_b32 s23, v242, 7
	v_readlane_b32 s24, v242, 8
	v_readlane_b32 s25, v242, 9
	v_readlane_b32 s26, v242, 10
	s_movk_i32 s19, 0xffee
	s_movk_i32 s20, 0xffed
	s_movk_i32 s21, 0xffdf
	s_movk_i32 s22, 0xffde
	s_movk_i32 s23, 0xffdd
	s_movk_i32 s24, 0xffcf
	s_movk_i32 s25, 0xffce
	s_movk_i32 s26, 0xffcd
	v_mov_b32_e32 v34, v3
	v_mov_b32_e32 v35, v3
	v_mov_b32_e32 v36, v3
	v_mov_b32_e32 v37, v3
	v_mov_b32_e32 v38, v3
	v_mov_b32_e32 v39, v3
	v_mov_b32_e32 v40, v3
	v_mov_b32_e32 v41, v3
	v_mov_b32_e32 v50, v3
	v_mov_b32_e32 v51, v3
	v_mov_b32_e32 v52, v3
	v_mov_b32_e32 v53, v3
	v_mov_b32_e32 v66, v3
	v_mov_b32_e32 v67, v3
	v_mov_b32_e32 v68, v3
	v_mov_b32_e32 v69, v3
	v_mov_b32_e32 v25, v3
	v_mov_b32_e32 v26, v3
	v_mov_b32_e32 v27, v3
	v_mov_b32_e32 v28, v3
	v_mov_b32_e32 v29, v3
	v_mov_b32_e32 v30, v3
	v_mov_b32_e32 v31, v3
	v_mov_b32_e32 v32, v3
	v_mov_b32_e32 v33, v3
	v_mov_b32_e32 v62, v3
	v_mov_b32_e32 v63, v3
	v_mov_b32_e32 v64, v3
	v_mov_b32_e32 v65, v3
	v_mov_b32_e32 v70, v3
	v_mov_b32_e32 v71, v3
	v_mov_b32_e32 v72, v3
	v_mov_b32_e32 v73, v3
	v_mov_b32_e32 v74, v3
	v_mov_b32_e32 v75, v3
	v_mov_b32_e32 v76, v3
	v_mov_b32_e32 v77, v3
	v_mov_b32_e32 v94, v3
	v_mov_b32_e32 v95, v3
	v_mov_b32_e32 v96, v3
	s_waitcnt vmcnt(1)
	v_mul_f32_e32 v6, 0xbfb8aa3b, v2
	v_fma_f32 v11, v2, s7, -v6
	v_rndne_f32_e32 v14, v6
	v_fmac_f32_e32 v11, 0xb2a5705f, v2
	v_sub_f32_e32 v6, v6, v14
	v_add_f32_e32 v6, v6, v11
	v_cvt_i32_f32_e32 v14, v14
	v_exp_f32_e32 v6, v6
	s_waitcnt vmcnt(0)
	v_mul_f32_e32 v7, 0xbfb8aa3b, v5
	v_cmp_nlt_f32_e32 vcc, s8, v2
	v_fma_f32 v15, v5, s7, -v7
	v_ldexp_f32 v6, v6, v14
	v_rndne_f32_e32 v16, v7
	v_cndmask_b32_e32 v6, 0, v6, vcc
	v_cmp_ngt_f32_e32 vcc, s9, v2
	v_fmac_f32_e32 v15, 0xb2a5705f, v5
	v_sub_f32_e32 v7, v7, v16
	v_cndmask_b32_e32 v2, v8, v6, vcc
	v_add_f32_e32 v7, v7, v15
	v_add_f32_e32 v14, 1.0, v2
	v_cvt_i32_f32_e32 v11, v16
	v_exp_f32_e32 v15, v7
	v_add_f32_e32 v16, -1.0, v14
	v_frexp_mant_f32_e32 v17, v14
	v_cvt_f64_f32_e32 v[6:7], v14
	v_sub_f32_e32 v18, v16, v14
	v_frexp_exp_i32_f64_e32 v6, v[6:7]
	v_cmp_gt_f32_e32 vcc, s10, v17
	v_sub_f32_e32 v16, v2, v16
	v_add_f32_e32 v7, 1.0, v18
	v_subbrev_co_u32_e32 v6, vcc, 0, v6, vcc
	v_add_f32_e32 v7, v16, v7
	v_sub_u32_e32 v16, 0, v6
	v_cvt_f32_i32_e32 v6, v6
	v_ldexp_f32 v14, v14, v16
	v_ldexp_f32 v7, v7, v16
	v_add_f32_e32 v16, -1.0, v14
	v_add_f32_e32 v17, 1.0, v14
	v_add_f32_e32 v18, 1.0, v16
	v_add_f32_e32 v19, -1.0, v17
	v_sub_f32_e32 v18, v14, v18
	v_sub_f32_e32 v14, v14, v19
	v_mul_f32_e32 v19, 0x3f317218, v6
	v_add_f32_e32 v18, v7, v18
	v_add_f32_e32 v7, v7, v14
	v_fma_f32 v14, v6, s6, -v19
	v_add_f32_e32 v20, v16, v18
	v_add_f32_e32 v21, v17, v7
	v_fmac_f32_e32 v14, 0xb102e308, v6
	v_sub_f32_e32 v6, v16, v20
	v_sub_f32_e32 v16, v17, v21
	v_rcp_f32_e32 v17, v21
	v_add_f32_e32 v22, v19, v14
	v_add_f32_e32 v7, v7, v16
	v_sub_f32_e32 v16, v22, v19
	v_sub_f32_e32 v14, v14, v16
	v_mul_f32_e32 v16, v20, v17
	v_add_f32_e32 v6, v18, v6
	v_mul_f32_e32 v18, v21, v16
	v_fma_f32 v19, v16, v21, -v18
	v_fmac_f32_e32 v19, v16, v7
	v_add_f32_e32 v23, v18, v19
	v_sub_f32_e32 v24, v20, v23
	v_sub_f32_e32 v18, v23, v18
	v_sub_f32_e32 v20, v20, v24
	v_sub_f32_e32 v18, v18, v19
	v_sub_f32_e32 v19, v20, v23
	v_add_f32_e32 v6, v6, v19
	v_add_f32_e32 v6, v18, v6
	v_add_f32_e32 v18, v24, v6
	v_mul_f32_e32 v19, v17, v18
	v_sub_f32_e32 v20, v24, v18
	v_mul_f32_e32 v23, v21, v19
	v_add_f32_e32 v6, v6, v20
	v_add_f32_e32 v20, v16, v19
	v_fma_f32 v21, v19, v21, -v23
	v_sub_f32_e32 v16, v20, v16
	v_fmac_f32_e32 v21, v19, v7
	v_sub_f32_e32 v7, v19, v16
	v_add_f32_e32 v16, v23, v21
	v_sub_f32_e32 v19, v16, v23
	v_sub_f32_e32 v23, v18, v16
	v_sub_f32_e32 v18, v18, v23
	v_sub_f32_e32 v16, v18, v16
	v_sub_f32_e32 v19, v19, v21
	v_add_f32_e32 v6, v6, v16
	v_add_f32_e32 v6, v19, v6
	v_add_f32_e32 v6, v23, v6
	v_mul_f32_e32 v6, v17, v6
	v_add_f32_e32 v6, v7, v6
	v_add_f32_e32 v7, v20, v6
	v_mul_f32_e32 v16, v7, v7
	v_fmamk_f32 v19, v16, 0x3e9b6dac, v9
	v_sub_f32_e32 v17, v7, v20
	v_ldexp_f32 v18, v7, 1
	v_mul_f32_e32 v7, v7, v16
	v_fmaak_f32 v16, v16, v19, 0x3f2aaada
	v_mul_f32_e32 v7, v7, v16
	v_add_f32_e32 v16, v18, v7
	v_sub_f32_e32 v6, v6, v17
	v_sub_f32_e32 v17, v16, v18
	v_ldexp_f32 v6, v6, 1
	v_sub_f32_e32 v7, v7, v17
	v_add_f32_e32 v6, v6, v7
	v_add_f32_e32 v7, v16, v6
	v_sub_f32_e32 v16, v7, v16
	v_add_f32_e32 v17, v22, v7
	v_sub_f32_e32 v6, v6, v16
	v_sub_f32_e32 v16, v17, v22
	v_sub_f32_e32 v18, v17, v16
	v_sub_f32_e32 v7, v7, v16
	v_add_f32_e32 v16, v14, v6
	v_sub_f32_e32 v18, v22, v18
	v_sub_f32_e32 v19, v16, v14
	v_add_f32_e32 v7, v7, v18
	v_sub_f32_e32 v18, v16, v19
	v_sub_f32_e32 v6, v6, v19
	v_sub_f32_e32 v14, v14, v18
	v_add_f32_e32 v7, v16, v7
	v_add_f32_e32 v6, v6, v14
	v_add_f32_e32 v14, v17, v7
	v_sub_f32_e32 v16, v14, v17
	v_sub_f32_e32 v7, v7, v16
	v_add_f32_e32 v6, v6, v7
	v_add_f32_e32 v6, v14, v6
	v_cmp_neq_f32_e32 vcc, s4, v2
	v_mov_b32_e32 v21, v3
	v_mov_b32_e32 v22, v3
	v_cndmask_b32_e32 v6, v8, v6, vcc
	v_cmp_lt_f32_e64 vcc, |v2|, s5
	v_mov_b32_e32 v23, v3
	v_mov_b32_e32 v24, v3
	v_cndmask_b32_e32 v2, v6, v2, vcc
	v_mul_f32_e32 v140, 0xbfb8aa3b, v2
	v_ldexp_f32 v2, v15, v11
	v_cmp_nlt_f32_e32 vcc, s8, v5
	s_mul_i32 s8, s1, 0x1200
	v_exp_f32_e64 v145, -v140
	v_cndmask_b32_e32 v2, 0, v2, vcc
	v_cmp_ngt_f32_e32 vcc, s9, v5
	v_mov_b32_e32 v97, v3
	v_readlane_b32 s27, v242, 11
	v_cndmask_b32_e32 v2, v8, v2, vcc
	v_add_f32_e32 v5, 1.0, v2
	v_add_f32_e32 v6, -1.0, v5
	v_sub_f32_e32 v7, v6, v5
	v_add_f32_e32 v7, 1.0, v7
	v_sub_f32_e32 v6, v2, v6
	v_add_f32_e32 v11, v6, v7
	v_frexp_mant_f32_e32 v14, v5
	v_cvt_f64_f32_e32 v[6:7], v5
	v_frexp_exp_i32_f64_e32 v6, v[6:7]
	v_cmp_gt_f32_e32 vcc, s10, v14
	v_readlane_b32 s28, v242, 12
	v_readlane_b32 s29, v242, 13
	v_subbrev_co_u32_e32 v6, vcc, 0, v6, vcc
	v_sub_u32_e32 v7, 0, v6
	v_ldexp_f32 v5, v5, v7
	v_ldexp_f32 v7, v11, v7
	v_add_f32_e32 v11, -1.0, v5
	v_add_f32_e32 v16, 1.0, v5
	v_add_f32_e32 v14, 1.0, v11
	v_add_f32_e32 v17, -1.0, v16
	v_sub_f32_e32 v14, v5, v14
	v_sub_f32_e32 v5, v5, v17
	v_add_f32_e32 v5, v7, v5
	v_add_f32_e32 v14, v7, v14
	v_add_f32_e32 v7, v16, v5
	v_rcp_f32_e32 v17, v7
	v_add_f32_e32 v15, v11, v14
	v_sub_f32_e32 v11, v11, v15
	v_add_f32_e32 v11, v14, v11
	v_sub_f32_e32 v14, v16, v7
	v_add_f32_e32 v5, v5, v14
	v_mul_f32_e32 v14, v15, v17
	v_mul_f32_e32 v16, v7, v14
	v_fma_f32 v18, v14, v7, -v16
	v_fmac_f32_e32 v18, v14, v5
	v_add_f32_e32 v19, v16, v18
	v_sub_f32_e32 v20, v15, v19
	v_sub_f32_e32 v15, v15, v20
	v_sub_f32_e32 v16, v19, v16
	v_sub_f32_e32 v15, v15, v19
	v_add_f32_e32 v11, v11, v15
	v_sub_f32_e32 v15, v16, v18
	v_add_f32_e32 v11, v15, v11
	v_add_f32_e32 v15, v20, v11
	v_mul_f32_e32 v16, v17, v15
	v_mul_f32_e32 v18, v7, v16
	v_fma_f32 v7, v16, v7, -v18
	v_fmac_f32_e32 v7, v16, v5
	v_sub_f32_e32 v5, v20, v15
	v_add_f32_e32 v5, v11, v5
	v_add_f32_e32 v11, v18, v7
	v_sub_f32_e32 v19, v15, v11
	v_sub_f32_e32 v15, v15, v19
	v_sub_f32_e32 v18, v11, v18
	v_sub_f32_e32 v11, v15, v11
	v_add_f32_e32 v5, v5, v11
	v_sub_f32_e32 v7, v18, v7
	v_add_f32_e32 v5, v7, v5
	v_add_f32_e32 v7, v14, v16
	v_add_f32_e32 v5, v19, v5
	v_sub_f32_e32 v11, v7, v14
	v_mul_f32_e32 v5, v17, v5
	v_sub_f32_e32 v11, v16, v11
	v_add_f32_e32 v5, v11, v5
	v_cvt_f32_i32_e32 v6, v6
	v_add_f32_e32 v11, v7, v5
	v_mul_f32_e32 v14, v11, v11
	v_fmac_f32_e32 v9, 0x3e9b6dac, v14
	v_fmac_f32_e32 v10, v14, v9
	v_mul_f32_e32 v9, 0x3f317218, v6
	v_fma_f32 v15, v6, s6, -v9
	v_fmac_f32_e32 v15, 0xb102e308, v6
	v_sub_f32_e32 v6, v11, v7
	v_sub_f32_e32 v5, v5, v6
	v_add_f32_e32 v6, v9, v15
	v_sub_f32_e32 v7, v6, v9
	v_ldexp_f32 v9, v11, 1
	v_mul_f32_e32 v11, v11, v14
	v_mul_f32_e32 v10, v11, v10
	v_add_f32_e32 v11, v9, v10
	v_sub_f32_e32 v9, v11, v9
	v_ldexp_f32 v5, v5, 1
	v_sub_f32_e32 v9, v10, v9
	v_add_f32_e32 v5, v5, v9
	v_add_f32_e32 v9, v11, v5
	v_sub_f32_e32 v10, v9, v11
	v_sub_f32_e32 v5, v5, v10
	v_add_f32_e32 v10, v6, v9
	v_sub_f32_e32 v11, v10, v6
	v_sub_f32_e32 v14, v10, v11
	v_sub_f32_e32 v7, v15, v7
	v_sub_f32_e32 v6, v6, v14
	v_sub_f32_e32 v9, v9, v11
	v_add_f32_e32 v6, v9, v6
	v_add_f32_e32 v9, v7, v5
	v_sub_f32_e32 v11, v9, v7
	v_sub_f32_e32 v14, v9, v11
	v_sub_f32_e32 v7, v7, v14
	v_sub_f32_e32 v5, v5, v11
	v_add_f32_e32 v6, v9, v6
	v_add_f32_e32 v5, v5, v7
	v_add_f32_e32 v7, v10, v6
	v_sub_f32_e32 v9, v7, v10
	v_sub_f32_e32 v6, v6, v9
	v_add_f32_e32 v5, v5, v6
	v_add_f32_e32 v5, v7, v5
	v_cmp_neq_f32_e32 vcc, s4, v2
	s_lshl_b32 s4, s0, 7
	v_ashrrev_i32_e32 v15, 4, v4
	v_cndmask_b32_e32 v5, v8, v5, vcc
	v_cmp_lt_f32_e64 vcc, |v2|, s5
	s_lshl_b32 s5, s1, 5
	s_add_u32 s0, s68, s16
	v_cndmask_b32_e32 v2, v5, v2, vcc
	v_mul_f32_e32 v149, 0xbfb8aa3b, v2
	v_mul_f32_e32 v2, 0x80000000, v140
	v_exp_f32_e32 v147, v2
	v_mul_f32_e32 v2, 0, v149
	v_exp_f32_e32 v148, v2
	v_mul_f32_e32 v2, -2.0, v140
	v_exp_f32_e32 v143, v2
	v_add_f32_e32 v2, v149, v149
	v_exp_f32_e32 v144, v2
	v_mul_f32_e32 v2, 0xc0400000, v140
	v_exp_f32_e32 v142, v2
	v_mul_f32_e32 v2, 0x40400000, v149
	v_exp_f32_e32 v141, v2
	v_or_b32_e32 v2, s5, v12
	v_add_u32_e32 v5, s3, v2
	s_addc_u32 s1, s69, 0
	v_and_b32_e32 v2, 48, v4
	v_lshl_add_u64 v[6:7], s[0:1], 0, v[2:3]
	v_mad_i64_i32 v[8:9], s[6:7], v5, s18, v[6:7]
	v_or_b32_e32 v5, 16, v5
	v_mad_i64_i32 v[6:7], s[6:7], v5, s18, v[6:7]
	global_load_dwordx4 v[90:93], v[8:9], off
	global_load_dwordx4 v[86:89], v[8:9], off offset:64
	global_load_dwordx4 v[82:85], v[8:9], off offset:128
	global_load_dwordx4 v[78:81], v[8:9], off offset:192
	global_load_dwordx4 v[58:61], v[6:7], off
	global_load_dwordx4 v[54:57], v[6:7], off offset:64
	global_load_dwordx4 v[46:49], v[6:7], off offset:128
	global_load_dwordx4 v[42:45], v[6:7], off offset:192
	v_add_u32_e32 v16, s3, v15
	v_mov_b64_e32 v[6:7], s[68:69]
	v_mad_i64_i32 v[8:9], s[6:7], v16, s18, v[6:7]
	v_lshlrev_b32_e32 v10, 4, v4
	v_lshl_add_u64 v[8:9], v[8:9], 0, s[16:17]
	v_and_b32_e32 v10, 0xf0, v10
	v_mov_b32_e32 v11, v3
	v_lshl_add_u64 v[8:9], v[8:9], 0, v[10:11]
	global_load_dwordx4 v[98:101], v[8:9], off offset:1024
	global_load_dwordx4 v[102:105], v[8:9], off offset:2048
	v_add_u32_e32 v8, 0x200, v4
	v_ashrrev_i32_e32 v8, 4, v8
	v_add_u32_e32 v9, s3, v8
	v_mad_i64_i32 v[6:7], s[6:7], v9, s18, v[6:7]
	v_lshl_add_u64 v[6:7], v[6:7], 0, s[16:17]
	v_lshl_add_u64 v[6:7], v[6:7], 0, v[10:11]
	global_load_dwordx4 v[106:109], v[6:7], off offset:1024
	global_load_dwordx4 v[110:113], v[6:7], off offset:2048
	v_exp_f32_e32 v146, v149
	v_lshlrev_b32_e32 v14, 3, v13
	v_lshlrev_b32_e32 v5, 3, v4
	v_lshlrev_b32_e32 v13, 2, v13
	v_bfe_u32 v4, v4, 2, 2
	s_add_i32 s6, s8, 0
	v_add_u32_e32 v6, 0, v10
	v_add_u32_e32 v7, 0, v2
	v_sub_u32_e32 v17, v12, v13
	v_or_b32_e32 v4, v14, v4
	v_and_b32_e32 v5, 24, v5
	s_movk_i32 s8, 0x110
	v_add_u32_e32 v150, s5, v17
	v_add_u32_e32 v17, s6, v14
	v_add_u32_e32 v2, s6, v2
	v_add_u32_e32 v5, 0, v5
	v_mad_u64_u32 v[136:137], s[6:7], v15, s8, v[6:7]
	v_mad_u64_u32 v[134:135], s[6:7], v8, s8, v[6:7]
	v_mul_u32_u24_e32 v6, 0x110, v12
	v_mul_u32_u24_e32 v8, 0x90, v12
	v_mul_u32_u24_e32 v4, 0x110, v4
	v_lshl_add_u64 v[138:139], s[0:1], 0, v[10:11]
	v_sub_u32_e32 v10, v13, v12
	v_subrev_u32_e32 v153, s5, v10
	v_add_u32_e32 v154, 64, v9
	v_add_u32_e32 v155, 64, v16
	s_movk_i32 s16, 0xffef
	v_add_u32_e32 v152, v7, v6
	v_add_u32_e32 v151, v17, v8
	v_add_u32_e32 v137, v2, v8
	v_add_u32_e32 v135, v5, v4
	v_mov_b32_e32 v156, v150
	v_mov_b32_e32 v2, v3
	v_mov_b32_e32 v4, v3
	v_mov_b32_e32 v5, v3
	v_mov_b32_e32 v6, v3
	v_mov_b32_e32 v7, v3
	v_mov_b32_e32 v8, v3
	v_mov_b32_e32 v9, v3
	v_mov_b32_e32 v10, v3
	v_mov_b32_e32 v12, v3
	v_mov_b32_e32 v13, v3
	v_mov_b32_e32 v14, v3
	v_mov_b32_e32 v15, v3
	v_mov_b32_e32 v16, v3
	v_mov_b32_e32 v17, v3
	v_mov_b32_e32 v18, v3
	v_mov_b32_e32 v19, v3
	v_mov_b32_e32 v20, v3
	v_readlane_b32 s30, v242, 14
	v_readlane_b32 s31, v242, 15

.LBB0_406:
	s_getreg_b32 s98, hwreg(HW_REG_XCC_ID, 0, 4)
	s_lshl_b32 s98, s98, 8
	v_mov_b32_e32 v1, 0x21160
	ds_read_b64 v[2:3], v1
	v_mov_b32_e32 v4, s98
	v_add_u32_e32 v4, 0x5400, v4
	v_mov_b32_e32 v5, 1
	global_atomic_add v6, v4, v5, s[54:55] sc0
	buffer_inv sc1
	v_add_u32_e32 v7, 0x1000, v4
	s_waitcnt lgkmcnt(0)
	v_mul_u32_u24_e32 v2, 4, v2
	v_mul_u32_u24_e32 v3, 4, v3
	s_waitcnt vmcnt(1)
	v_add_u32_e32 v6, 1, v6
	v_cmp_ne_u32_e32 vcc, v6, v2
	s_cbranch_vccnz .Lgb4_4_follow
	buffer_wbl2 sc1
	s_waitcnt vmcnt(0)
	v_mov_b32_e32 v4, 0x7400
	global_atomic_add v6, v4, v5, s[54:55] sc0
	s_waitcnt vmcnt(0)
	v_add_u32_e32 v6, 1, v6
	v_cmp_ne_u32_e32 vcc, v6, v3
	s_cbranch_vccnz .Lgb4_4_follow
	v_mov_b32_e32 v4, 0x6400
	global_atomic_add v4, v5, s[54:55]
	global_atomic_add v4, v5, s[54:55] offset:256
	global_atomic_add v4, v5, s[54:55] offset:512
	global_atomic_add v4, v5, s[54:55] offset:768
	global_atomic_add v4, v5, s[54:55] offset:1024
	global_atomic_add v4, v5, s[54:55] offset:1280
	global_atomic_add v4, v5, s[54:55] offset:1536
	global_atomic_add v4, v5, s[54:55] offset:1792
	global_atomic_add v4, v5, s[54:55] offset:2048
	global_atomic_add v4, v5, s[54:55] offset:2304
	global_atomic_add v4, v5, s[54:55] offset:2560
	global_atomic_add v4, v5, s[54:55] offset:2816
	global_atomic_add v4, v5, s[54:55] offset:3072
	global_atomic_add v4, v5, s[54:55] offset:3328
	global_atomic_add v4, v5, s[54:55] offset:3584
	global_atomic_add v4, v5, s[54:55] offset:3840
	s_branch .Lgb4_4_acq

.Lgb4_4_gen:
	global_load_dword v6, v7, s[54:55] sc1
	s_waitcnt vmcnt(0)
	v_cmp_ge_u32_e32 vcc, v6, v2
	s_cbranch_vccnz .Lgb4_4_acq
	s_add_i32 s99, s99, 1
	s_cmp_gt_u32 s99, 0x40000
	s_cbranch_scc1 .Lgb4_4_acq
	s_sleep 1
	s_branch .Lgb4_4_gen
.Lgb4_4_acq:
	s_waitcnt vmcnt(0)
.LBB0_442:
	s_or_b64 exec, exec, s[6:7]
	v_readlane_b32 s0, v242, 38
	s_add_u32 s84, s54, 0x3400000
	v_mov_b32_e32 v215, v0
	v_readlane_b32 s1, v242, 39
	s_addc_u32 s85, s55, 0
	s_waitcnt lgkmcnt(0)
	s_barrier
	s_and_b64 vcc, exec, s[0:1]
	v_readfirstlane_b32 s3, v215
	s_cbranch_vccnz .LBB0_497
	v_lshlrev_b32_e32 v1, 4, v215
	v_add_u32_e32 v2, 0x2000, v1
	v_ashrrev_i32_e32 v3, 31, v2
	v_lshrrev_b32_e32 v3, 22, v3
	v_add_u32_e32 v3, v2, v3
	v_ashrrev_i32_e32 v10, 10, v3
	v_mul_i32_i24_e32 v3, 0x400, v10
	v_sub_u32_e32 v2, v2, v3
	v_lshrrev_b32_e32 v3, 4, v2
	v_bitop3_b32 v2, v3, v2, 32 bitop3:0x6c
	v_ashrrev_i32_e32 v3, 31, v2
	v_lshrrev_b32_e32 v3, 26, v3
	v_add_u32_e32 v3, v2, v3
	v_lshlrev_b32_e32 v4, 3, v10
	v_ashrrev_i32_e32 v11, 6, v3
	v_and_b32_e32 v4, -16, v4
	v_add_u32_e32 v4, v11, v4
	v_and_b32_e32 v5, 3, v11
	s_mov_b32 s0, 0x1fffe0
	v_lshrrev_b32_e32 v6, 2, v4
	v_lshlrev_b32_e32 v7, 1, v4
	v_and_b32_e32 v3, 0xc0, v3
	v_and_or_b32 v5, v4, s0, v5
	v_and_b32_e32 v6, 4, v6
	v_and_b32_e32 v7, 24, v7
	v_sub_u32_e32 v2, v2, v3
	v_mov_b32_e32 v3, 1
	v_or3_b32 v5, v5, v6, v7
	v_lshlrev_b32_e32 v6, 5, v10
	v_ashrrev_i16_sdwa v2, v3, sext(v2) dst_sel:DWORD dst_unused:UNUSED_PAD src0_sel:DWORD src1_sel:BYTE_0
	v_and_b32_e32 v6, 32, v6
	v_bfe_i32 v12, v2, 0, 16
	v_add_lshl_u32 v2, v6, v12, 1
	v_lshl_add_u32 v130, v5, 11, v2
	v_lshl_add_u32 v132, v4, 11, v2
	v_bfe_i32 v2, v215, 27, 1
	v_lshrrev_b32_e32 v2, 22, v2
	v_add_u32_e32 v2, v1, v2
	v_and_b32_e32 v2, 0xfffffc00, v2
	v_sub_u32_e32 v1, v1, v2
	v_lshrrev_b32_e32 v2, 4, v1
	v_ashrrev_i32_e32 v4, 31, v215
	v_bitop3_b32 v1, v2, v1, 32 bitop3:0x6c
	v_lshrrev_b32_e32 v4, 26, v4
	v_ashrrev_i32_e32 v2, 31, v1
	v_add_u32_e32 v4, v215, v4
	v_lshrrev_b32_e32 v2, 26, v2
	v_ashrrev_i32_e32 v14, 6, v4
	v_add_u32_e32 v2, v1, v2
	v_lshlrev_b32_e32 v4, 3, v14
	v_ashrrev_i32_e32 v13, 6, v2
	v_and_b32_e32 v4, -16, v4
	v_add_u32_e32 v4, v13, v4
	v_and_b32_e32 v5, 3, v13
	s_ashr_i32 s62, s38, 31
	v_and_or_b32 v5, v4, s0, v5
	s_lshr_b32 s0, s62, 29
	s_add_i32 s0, s38, s0
	s_ashr_i32 s34, s3, 6
	s_ashr_i32 s1, s0, 3
	s_and_b32 s0, s0, -8
	s_ashr_i32 s4, s3, 8
	s_lshl_b32 s37, s34, 10
	s_sub_i32 s0, s38, s0
	s_cmp_lt_i32 s0, 0
	s_cselect_b32 s5, 25, 24
	s_mul_i32 s0, s0, s5
	s_add_i32 s0, s0, s1
	s_mul_hi_i32 s1, s0, 0x2aaaaaab
	s_lshr_b32 s5, s1, 31
	s_ashr_i32 s1, s1, 2
	s_add_i32 s1, s1, s5
	s_mul_i32 s5, s1, 6
	s_mul_i32 s1, s1, 24
	s_sub_i32 s0, s0, s1
	s_bfe_i32 s1, s0, 0x80000
	s_mul_i32 s1, s1, 43
	s_bfe_u32 s6, s1, 0x1000f
	s_bfe_u32 s1, s1, 0x80008
	s_add_i32 s6, s1, s6
	s_mul_i32 s1, s6, 6
	s_sub_i32 s0, s0, s1
	s_sext_i32_i8 s0, s0
	v_lshrrev_b32_e32 v6, 2, v4
	v_lshlrev_b32_e32 v7, 1, v4
	v_and_b32_e32 v2, 0xc0, v2
	s_add_i32 s86, s5, s0
	v_and_b32_e32 v6, 4, v6
	v_and_b32_e32 v7, 24, v7
	v_sub_u32_e32 v1, v1, v2
	s_ashr_i32 s87, s86, 31
	s_bfe_i64 s[8:9], s[6:7], 0x80000
	v_or3_b32 v5, v5, v6, v7
	v_lshlrev_b32_e32 v6, 5, v14
	v_ashrrev_i16_sdwa v1, v3, sext(v1) dst_sel:DWORD dst_unused:UNUSED_PAD src0_sel:DWORD src1_sel:BYTE_0
	s_lshl_b64 s[0:1], s[86:87], 19
	s_lshl_b64 s[8:9], s[8:9], 19
	v_and_b32_e32 v6, 32, v6
	v_bfe_i32 v15, v1, 0, 16
	s_add_u32 s26, s70, s8
	v_add_lshl_u32 v1, v6, v15, 1
	s_addc_u32 s27, s71, s9
	s_add_i32 s63, s37, 0
	v_lshl_add_u32 v134, v5, 11, v1
	s_add_i32 m0, s63, 0x10000
	v_lshl_add_u32 v136, v4, 11, v1
	global_load_lds_dwordx4 v134, s[26:27]
	s_add_i32 m0, s63, 0x12000
	s_add_u32 s8, s26, 0x40000
	global_load_lds_dwordx4 v130, s[26:27]
	s_addc_u32 s9, s27, 0
	s_add_i32 m0, s63, 0x14000
	v_mov_b32_e32 v135, 0
	global_load_lds_dwordx4 v134, s[8:9]
	s_add_i32 m0, s63, 0x16000
	s_add_u32 s10, s60, s0
	s_addc_u32 s11, s61, s1
	s_add_i32 s0, s63, 0x2000
	global_load_lds_dwordx4 v130, s[8:9]
	s_mov_b32 m0, s63
	s_add_u32 s8, s10, 0x40000
	global_load_lds_dwordx4 v136, s[10:11]
	s_mov_b32 m0, s0
	s_addc_u32 s9, s11, 0
	s_add_i32 s1, s63, 0x4000
	global_load_lds_dwordx4 v132, s[10:11]
	s_mov_b32 m0, s1
	s_add_i32 s64, s63, 0x6000
	global_load_lds_dwordx4 v136, s[8:9]
	s_mov_b32 m0, s64
	v_mov_b32_e32 v131, v135
	global_load_lds_dwordx4 v132, s[8:9]
	v_mov_b32_e32 v137, v135
	v_mov_b32_e32 v133, v135
	s_mov_b32 s65, 0
	v_lshl_add_u64 v[8:9], s[26:27], 0, v[134:135]
	v_lshl_add_u64 v[6:7], s[26:27], 0, v[130:131]
	v_lshl_add_u64 v[4:5], s[10:11], 0, v[136:137]
	s_cmp_lg_u32 s4, 1
	v_lshl_add_u64 v[2:3], s[10:11], 0, v[132:133]
	s_cbranch_scc1 .LBB0_445
	s_barrier

.LBB0_536:
	s_getreg_b32 s98, hwreg(HW_REG_XCC_ID, 0, 4)
	s_lshl_b32 s98, s98, 8
	v_mov_b32_e32 v1, 0x21160
	ds_read_b64 v[2:3], v1
	v_mov_b32_e32 v4, s98
	v_add_u32_e32 v4, 0x5400, v4
	v_mov_b32_e32 v5, 1
	global_atomic_add v6, v4, v5, s[54:55] sc0
	buffer_inv sc1
	v_add_u32_e32 v7, 0x1000, v4
	s_waitcnt lgkmcnt(0)
	v_mul_u32_u24_e32 v2, 5, v2
	v_mul_u32_u24_e32 v3, 5, v3
	s_waitcnt vmcnt(1)
	v_add_u32_e32 v6, 1, v6
	v_cmp_ne_u32_e32 vcc, v6, v2
	s_cbranch_vccnz .Lgb4_5_follow
	buffer_wbl2 sc1
	s_waitcnt vmcnt(0)
	v_mov_b32_e32 v4, 0x7400
	global_atomic_add v6, v4, v5, s[54:55] sc0
	s_waitcnt vmcnt(0)
	v_add_u32_e32 v6, 1, v6
	v_cmp_ne_u32_e32 vcc, v6, v3
	s_cbranch_vccnz .Lgb4_5_follow
	v_mov_b32_e32 v4, 0x6400
	global_atomic_add v4, v5, s[54:55]
	global_atomic_add v4, v5, s[54:55] offset:256
	global_atomic_add v4, v5, s[54:55] offset:512
	global_atomic_add v4, v5, s[54:55] offset:768
	global_atomic_add v4, v5, s[54:55] offset:1024
	global_atomic_add v4, v5, s[54:55] offset:1280
	global_atomic_add v4, v5, s[54:55] offset:1536
	global_atomic_add v4, v5, s[54:55] offset:1792
	global_atomic_add v4, v5, s[54:55] offset:2048
	global_atomic_add v4, v5, s[54:55] offset:2304
	global_atomic_add v4, v5, s[54:55] offset:2560
	global_atomic_add v4, v5, s[54:55] offset:2816
	global_atomic_add v4, v5, s[54:55] offset:3072
	global_atomic_add v4, v5, s[54:55] offset:3328
	global_atomic_add v4, v5, s[54:55] offset:3584
	global_atomic_add v4, v5, s[54:55] offset:3840
	s_branch .Lgb4_5_acq

.Lgb4_5_gen:
	global_load_dword v6, v7, s[54:55] sc1
	s_waitcnt vmcnt(0)
	v_cmp_ge_u32_e32 vcc, v6, v2
	s_cbranch_vccnz .Lgb4_5_acq
	s_add_i32 s99, s99, 1
	s_cmp_gt_u32 s99, 0x40000
	s_cbranch_scc1 .Lgb4_5_acq
	s_sleep 1
	s_branch .Lgb4_5_gen
.Lgb4_5_acq:
	s_waitcnt vmcnt(0)
.LBB0_572:
	s_or_b64 exec, exec, s[6:7]
	v_mov_b32_e32 v12, v0
	s_waitcnt lgkmcnt(0)
	s_barrier
	s_cmpk_gt_i32 s38, 0x2ff
	v_readfirstlane_b32 s4, v12
	s_cbranch_scc1 .LBB0_588
	v_lshlrev_b32_e32 v1, 4, v12
	v_add_u32_e32 v2, 0x2000, v1
	v_ashrrev_i32_e32 v3, 31, v2
	v_lshrrev_b32_e32 v3, 22, v3
	v_add_u32_e32 v3, v2, v3
	v_ashrrev_i32_e32 v10, 10, v3
	v_mul_i32_i24_e32 v3, 0x400, v10
	v_sub_u32_e32 v2, v2, v3
	v_lshrrev_b32_e32 v3, 4, v2
	v_bitop3_b32 v2, v3, v2, 32 bitop3:0x6c
	v_ashrrev_i32_e32 v3, 31, v2
	v_lshrrev_b32_e32 v3, 26, v3
	v_add_u32_e32 v3, v2, v3
	v_lshlrev_b32_e32 v4, 3, v10
	v_ashrrev_i32_e32 v11, 6, v3
	v_and_b32_e32 v4, -16, v4
	v_add_u32_e32 v4, v11, v4
	v_and_b32_e32 v5, 3, v11
	s_mov_b32 s0, 0x1fffe0
	v_lshrrev_b32_e32 v6, 2, v4
	v_lshlrev_b32_e32 v7, 1, v4
	v_and_b32_e32 v3, 0xc0, v3
	v_and_or_b32 v5, v4, s0, v5
	v_and_b32_e32 v6, 4, v6
	v_and_b32_e32 v7, 24, v7
	v_sub_u32_e32 v2, v2, v3
	v_mov_b32_e32 v3, 1
	v_or3_b32 v5, v5, v6, v7
	v_lshlrev_b32_e32 v6, 5, v10
	v_ashrrev_i16_sdwa v2, v3, sext(v2) dst_sel:DWORD dst_unused:UNUSED_PAD src0_sel:DWORD src1_sel:BYTE_0
	v_and_b32_e32 v6, 32, v6
	v_bfe_i32 v13, v2, 0, 16
	v_add_lshl_u32 v2, v6, v13, 1
	v_lshl_add_u32 v146, v5, 11, v2
	v_lshl_add_u32 v148, v4, 11, v2
	v_bfe_i32 v2, v12, 27, 1
	v_lshrrev_b32_e32 v2, 22, v2
	v_add_u32_e32 v2, v1, v2
	v_and_b32_e32 v2, 0xfffffc00, v2
	v_sub_u32_e32 v1, v1, v2
	v_lshrrev_b32_e32 v2, 4, v1
	v_ashrrev_i32_e32 v4, 31, v12
	v_bitop3_b32 v1, v2, v1, 32 bitop3:0x6c
	v_lshrrev_b32_e32 v4, 26, v4
	v_ashrrev_i32_e32 v2, 31, v1
	v_add_u32_e32 v4, v12, v4
	v_lshrrev_b32_e32 v2, 26, v2
	v_ashrrev_i32_e32 v15, 6, v4
	v_add_u32_e32 v2, v1, v2
	v_lshlrev_b32_e32 v4, 3, v15
	v_ashrrev_i32_e32 v14, 6, v2
	v_and_b32_e32 v4, -16, v4
	v_add_u32_e32 v4, v14, v4
	v_and_b32_e32 v5, 3, v14
	v_and_or_b32 v5, v4, s0, v5
	s_ashr_i32 s0, s38, 31
	s_lshr_b32 s1, s0, 29
	s_add_i32 s1, s38, s1
	s_ashr_i32 s7, s4, 6
	s_ashr_i32 s6, s1, 3
	s_and_b32 s1, s1, -8
	s_ashr_i32 s5, s4, 8
	s_lshl_b32 s3, s7, 10
	s_sub_i32 s14, s38, s1
	s_cmp_lt_i32 s14, 0
	s_movk_i32 s1, 0x61
	s_cselect_b32 s15, s1, 0x60
	s_mul_i32 s14, s14, s15
	s_add_i32 s14, s14, s6
	s_mul_hi_i32 s6, s14, 0x2aaaaaab
	s_lshr_b32 s15, s6, 31
	s_ashr_i32 s6, s6, 4
	s_add_i32 s6, s6, s15
	s_mul_i32 s15, s6, 6
	s_mulk_i32 s6, 0x60
	s_sub_i32 s14, s14, s6
	s_bfe_i32 s6, s14, 0x80000
	s_mul_i32 s6, s6, 43
	s_bfe_u32 s16, s6, 0x1000f
	s_bfe_u32 s6, s6, 0x80008
	s_add_i32 s6, s6, s16
	s_mul_i32 s16, s6, 6
	s_sub_i32 s14, s14, s16
	s_sext_i32_i8 s14, s14
	v_lshrrev_b32_e32 v6, 2, v4
	v_lshlrev_b32_e32 v7, 1, v4
	v_and_b32_e32 v2, 0xc0, v2
	s_add_i32 s40, s15, s14
	v_and_b32_e32 v6, 4, v6
	v_and_b32_e32 v7, 24, v7
	v_sub_u32_e32 v1, v1, v2
	s_ashr_i32 s41, s40, 31
	s_bfe_i64 s[16:17], s[6:7], 0x80000
	v_or3_b32 v5, v5, v6, v7
	v_lshlrev_b32_e32 v6, 5, v15
	v_ashrrev_i16_sdwa v1, v3, sext(v1) dst_sel:DWORD dst_unused:UNUSED_PAD src0_sel:DWORD src1_sel:BYTE_0
	s_lshl_b64 s[14:15], s[40:41], 19
	s_lshl_b64 s[16:17], s[16:17], 19
	v_and_b32_e32 v6, 32, v6
	v_bfe_i32 v16, v1, 0, 16
	s_add_u32 s56, s88, s16
	v_add_lshl_u32 v1, v6, v16, 1
	s_addc_u32 s57, s89, s17
	s_add_i32 s41, s3, 0
	v_lshl_add_u32 v150, v5, 11, v1
	s_add_i32 m0, s41, 0x10000
	v_lshl_add_u32 v152, v4, 11, v1
	global_load_lds_dwordx4 v150, s[56:57]
	s_add_i32 m0, s41, 0x12000
	s_add_u32 s16, s56, 0x40000
	global_load_lds_dwordx4 v146, s[56:57]
	s_addc_u32 s17, s57, 0
	s_add_i32 m0, s41, 0x14000
	v_mov_b32_e32 v151, 0
	global_load_lds_dwordx4 v150, s[16:17]
	s_add_i32 m0, s41, 0x16000
	s_add_u32 s44, s66, s14
	s_addc_u32 s45, s67, s15
	s_add_i32 s60, s41, 0x2000
	global_load_lds_dwordx4 v146, s[16:17]
	s_mov_b32 m0, s41
	s_add_u32 s14, s44, 0x40000
	global_load_lds_dwordx4 v152, s[44:45]
	s_mov_b32 m0, s60
	s_addc_u32 s15, s45, 0
	s_add_i32 s61, s41, 0x4000
	global_load_lds_dwordx4 v148, s[44:45]
	s_mov_b32 m0, s61
	s_add_i32 s62, s41, 0x6000
	global_load_lds_dwordx4 v152, s[14:15]
	s_mov_b32 m0, s62
	v_mov_b32_e32 v147, v151
	global_load_lds_dwordx4 v148, s[14:15]
	v_mov_b32_e32 v153, v151
	v_mov_b32_e32 v149, v151
	s_cmp_eq_u32 s5, 1
	s_mov_b32 s63, 0
	v_lshl_add_u64 v[8:9], s[56:57], 0, v[150:151]
	v_lshl_add_u64 v[6:7], s[56:57], 0, v[146:147]
	v_lshl_add_u64 v[2:3], s[44:45], 0, v[152:153]
	s_cselect_b64 s[14:15], -1, 0
	s_cmp_lg_u32 s5, 1
	v_lshl_add_u64 v[4:5], s[44:45], 0, v[148:149]
	s_cbranch_scc1 .LBB0_575
	s_barrier

.LBB0_604:
	s_getreg_b32 s98, hwreg(HW_REG_XCC_ID, 0, 4)
	s_lshl_b32 s98, s98, 8
	v_mov_b32_e32 v1, 0x21160
	ds_read_b64 v[2:3], v1
	v_mov_b32_e32 v4, s98
	v_add_u32_e32 v4, 0x5400, v4
	v_mov_b32_e32 v5, 1
	global_atomic_add v6, v4, v5, s[54:55] sc0
	buffer_inv sc1
	v_add_u32_e32 v7, 0x1000, v4
	s_waitcnt lgkmcnt(0)
	v_mul_u32_u24_e32 v2, 6, v2
	v_mul_u32_u24_e32 v3, 6, v3
	s_waitcnt vmcnt(1)
	v_add_u32_e32 v6, 1, v6
	v_cmp_ne_u32_e32 vcc, v6, v2
	s_cbranch_vccnz .Lgb4_6_follow
	buffer_wbl2 sc1
	s_waitcnt vmcnt(0)
	v_mov_b32_e32 v4, 0x7400
	global_atomic_add v6, v4, v5, s[54:55] sc0
	s_waitcnt vmcnt(0)
	v_add_u32_e32 v6, 1, v6
	v_cmp_ne_u32_e32 vcc, v6, v3
	s_cbranch_vccnz .Lgb4_6_follow
	v_mov_b32_e32 v4, 0x6400
	global_atomic_add v4, v5, s[54:55]
	global_atomic_add v4, v5, s[54:55] offset:256
	global_atomic_add v4, v5, s[54:55] offset:512
	global_atomic_add v4, v5, s[54:55] offset:768
	global_atomic_add v4, v5, s[54:55] offset:1024
	global_atomic_add v4, v5, s[54:55] offset:1280
	global_atomic_add v4, v5, s[54:55] offset:1536
	global_atomic_add v4, v5, s[54:55] offset:1792
	global_atomic_add v4, v5, s[54:55] offset:2048
	global_atomic_add v4, v5, s[54:55] offset:2304
	global_atomic_add v4, v5, s[54:55] offset:2560
	global_atomic_add v4, v5, s[54:55] offset:2816
	global_atomic_add v4, v5, s[54:55] offset:3072
	global_atomic_add v4, v5, s[54:55] offset:3328
	global_atomic_add v4, v5, s[54:55] offset:3584
	global_atomic_add v4, v5, s[54:55] offset:3840
	s_branch .Lgb4_6_acq

.Lgb4_6_gen:
	global_load_dword v6, v7, s[54:55] sc1
	s_waitcnt vmcnt(0)
	v_cmp_ge_u32_e32 vcc, v6, v2
	s_cbranch_vccnz .Lgb4_6_acq
	s_add_i32 s99, s99, 1
	s_cmp_gt_u32 s99, 0x40000
	s_cbranch_scc1 .Lgb4_6_acq
	s_sleep 1
	s_branch .Lgb4_6_gen
.Lgb4_6_acq:
	s_waitcnt vmcnt(0)
.LBB0_640:
	s_or_b64 exec, exec, s[6:7]
	v_readlane_b32 s0, v242, 38
	v_readlane_b32 s1, v242, 39
	s_waitcnt lgkmcnt(0)
	s_barrier
	s_and_b64 vcc, exec, s[0:1]
	v_readfirstlane_b32 s34, v0
	v_lshlrev_b32_e32 v1, 4, v0
	v_add_u32_e32 v2, 0x2000, v1
	v_ashrrev_i32_e32 v3, 31, v2
	v_lshrrev_b32_e32 v3, 22, v3
	v_add_u32_e32 v3, v2, v3
	v_ashrrev_i32_e32 v10, 10, v3
	v_mul_i32_i24_e32 v3, 0x400, v10
	v_sub_u32_e32 v2, v2, v3
	v_lshrrev_b32_e32 v3, 4, v2
	v_bitop3_b32 v2, v3, v2, 32 bitop3:0x6c
	v_ashrrev_i32_e32 v3, 31, v2
	v_lshrrev_b32_e32 v3, 26, v3
	v_add_u32_e32 v3, v2, v3
	v_lshlrev_b32_e32 v4, 3, v10
	v_ashrrev_i32_e32 v11, 6, v3
	v_and_b32_e32 v4, -16, v4
	v_add_u32_e32 v4, v11, v4
	v_and_b32_e32 v5, 3, v11
	s_mov_b32 s0, 0x7ffe0
	v_lshrrev_b32_e32 v6, 2, v4
	v_lshlrev_b32_e32 v7, 1, v4
	v_and_b32_e32 v3, 0xc0, v3
	v_and_or_b32 v5, v4, s0, v5
	v_and_b32_e32 v6, 4, v6
	v_and_b32_e32 v7, 24, v7
	v_sub_u32_e32 v2, v2, v3
	v_mov_b32_e32 v3, 1
	v_or3_b32 v5, v5, v6, v7
	v_lshlrev_b32_e32 v6, 5, v10
	v_ashrrev_i16_sdwa v2, v3, sext(v2) dst_sel:DWORD dst_unused:UNUSED_PAD src0_sel:DWORD src1_sel:BYTE_0
	v_and_b32_e32 v6, 32, v6
	v_bfe_i32 v12, v2, 0, 16
	v_add_lshl_u32 v2, v6, v12, 1
	v_lshl_add_u32 v122, v5, 13, v2
	v_lshl_add_u32 v124, v4, 13, v2
	v_add_u32_e32 v124, 0xfffe0000, v124
	v_bfe_i32 v2, v0, 27, 1
	v_lshrrev_b32_e32 v2, 22, v2
	v_add_u32_e32 v2, v1, v2
	v_and_b32_e32 v2, 0xfffffc00, v2
	v_sub_u32_e32 v1, v1, v2
	v_lshrrev_b32_e32 v2, 4, v1
	v_ashrrev_i32_e32 v4, 31, v0
	v_bitop3_b32 v1, v2, v1, 32 bitop3:0x6c
	v_lshrrev_b32_e32 v4, 26, v4
	v_ashrrev_i32_e32 v2, 31, v1
	v_add_u32_e32 v4, v0, v4
	v_lshrrev_b32_e32 v2, 26, v2
	v_ashrrev_i32_e32 v14, 6, v4
	v_add_u32_e32 v2, v1, v2
	v_lshlrev_b32_e32 v4, 3, v14
	v_ashrrev_i32_e32 v13, 6, v2
	v_and_b32_e32 v4, -16, v4
	v_add_u32_e32 v4, v13, v4
	v_and_b32_e32 v5, 3, v13
	s_ashr_i32 s36, s38, 31
	v_and_or_b32 v5, v4, s0, v5
	s_lshr_b32 s0, s36, 29
	s_add_i32 s0, s38, s0
	s_ashr_i32 s3, s34, 6
	s_ashr_i32 s1, s0, 3
	s_and_b32 s0, s0, -8
	s_ashr_i32 s11, s34, 8
	s_lshl_b32 s35, s3, 10
	s_sub_i32 s0, s38, s0
	s_cmp_lt_i32 s0, 0
	s_cselect_b32 s4, 25, 24
	s_mul_i32 s0, s0, s4
	s_add_i32 s0, s0, s1
	s_mul_hi_i32 s1, s0, 0x2aaaaaab
	s_lshr_b32 s4, s1, 31
	s_ashr_i32 s1, s1, 2
	s_add_i32 s1, s1, s4
	s_mul_i32 s4, s1, 6
	s_mul_i32 s1, s1, 24
	s_sub_i32 s1, s0, s1
	s_mul_i32 s0, s1, 43
	s_bfe_u32 s5, s0, 0x1000f
	s_bfe_u32 s0, s0, 0x80008
	s_add_i32 s0, s0, s5
	s_mul_i32 s5, s0, 6
	s_sub_i32 s1, s1, s5
	s_sext_i32_i8 s1, s1
	v_lshrrev_b32_e32 v6, 2, v4
	v_lshlrev_b32_e32 v7, 1, v4
	v_and_b32_e32 v2, 0xc0, v2
	s_add_i32 s6, s4, s1
	v_and_b32_e32 v6, 4, v6
	v_and_b32_e32 v7, 24, v7
	v_sub_u32_e32 v1, v1, v2
	s_lshr_b32 s1, s38, 3
	s_and_b32 s0, s1, 3
	s_lshr_b32 s1, s1, 2
	s_and_b32 s6, s38, 7
	s_lshl_b32 s6, s6, 3
	s_add_i32 s6, s6, s1
	s_ashr_i32 s7, s6, 31
	s_bfe_i64 s[14:15], s[0:1], 0x80000
	v_or3_b32 v5, v5, v6, v7
	v_lshlrev_b32_e32 v6, 5, v14
	v_ashrrev_i16_sdwa v1, v3, sext(v1) dst_sel:DWORD dst_unused:UNUSED_PAD src0_sel:DWORD src1_sel:BYTE_0
	s_mul_i32 s4, s6, 0x180000
	s_mov_b32 s5, 0
	s_lshl_b64 s[14:15], s[14:15], 21
	v_and_b32_e32 v6, 32, v6
	v_bfe_i32 v15, v1, 0, 16
	s_add_u32 s26, s86, s14
	v_add_lshl_u32 v1, v6, v15, 1
	s_addc_u32 s27, s87, s15
	s_add_i32 s37, s35, 0
	v_lshl_add_u32 v134, v5, 13, v1
	s_add_i32 m0, s37, 0x10000
	v_lshl_add_u32 v136, v4, 13, v1
	global_load_lds_dwordx4 v134, s[26:27]
	s_add_i32 m0, s37, 0x12000
	s_add_u32 s14, s26, 0x100000
	global_load_lds_dwordx4 v122, s[26:27]
	s_addc_u32 s15, s27, 0
	s_add_i32 m0, s37, 0x14000
	v_mov_b32_e32 v135, 0
	global_load_lds_dwordx4 v134, s[14:15]
	s_add_i32 m0, s37, 0x16000
	v_mov_b32_e32 v123, v135
	global_load_lds_dwordx4 v122, s[14:15]
	s_add_u32 s14, s68, s4
	s_addc_u32 s15, s69, s5
	s_add_i32 s41, s37, 0x2000
	s_mov_b32 m0, s37
	s_add_u32 s4, s14, 0xc0000
	global_load_lds_dwordx4 v136, s[14:15]
	s_mov_b32 m0, s41
	s_addc_u32 s5, s15, 0
	s_add_i32 s42, s37, 0x4000
	global_load_lds_dwordx4 v124, s[14:15]
	s_mov_b32 m0, s42
	s_add_i32 s43, s37, 0x6000
	global_load_lds_dwordx4 v136, s[4:5]
	s_mov_b32 m0, s43
	v_mov_b32_e32 v137, v135
	global_load_lds_dwordx4 v124, s[4:5]
	v_mov_b32_e32 v125, v135
	s_mov_b32 s44, 0
	v_lshl_add_u64 v[8:9], s[26:27], 0, v[134:135]
	v_lshl_add_u64 v[6:7], s[26:27], 0, v[122:123]
	v_lshl_add_u64 v[4:5], s[14:15], 0, v[136:137]
	s_cmp_lg_u32 s11, 1
	v_lshl_add_u64 v[2:3], s[14:15], 0, v[124:125]
	s_cbranch_scc1 .LBB0_643
	s_barrier
